# dropped the redundant tile-epilogue head barrier in FFN1/FFN2/WOUT (LDS-DMA double buffer makes it unnecessary), on top of the FFN1 epilogue rewrite
# baseline (speedup 1.0000x reference)
; DI int TIDX() { int t = threadIdx.x; asm volatile("" : "+v"(t)); return t; }
; template <class F>
; DI void epi_foreach(f32x16 (&acc)[2][2], int m0, int n0, F f) {
;   const int lane = TIDX() & 63, w = TIDX() >> 6, wm = w >> 1, wn = w & 1, hh = lane >> 5, c = lane & 31;
; #pragma unroll
;   for (int mi = 0; mi < 2; ++mi)
; #pragma unroll
;     for (int ni = 0; ni < 2; ++ni) f(m0 + wm * 64 + mi * 32 + 4 * hh, n0 + wn * 64 + ni * 32 + c, acc[mi][ni]);
; }
; DI void phase_gemm_plain(const h16* A, int lda, const h16* Bt, int K, h16* C, int ldc, int mt0, int mt1, int ntn, char* smem) {
;     ...
;     epi_foreach(acc, m0, n0, [&](int rbase, int n, const f32x16& v) {
; #pragma unroll
;       for (int i = 0; i < 16; ++i) C[(size_t)EROW(rbase, i) * ldc + n] = (h16)v[i];
;     });
.LBB0_57:
	v_mov_b32_e32 v0, v203
	s_waitcnt vmcnt(0)
	v_mov_b32_e32 v66, v203
	s_nop 7
	s_nop 7
	s_nop 7
	s_nop 4
	v_cvt_f16_f32_e32 v20, v20
	v_and_b32_e32 v67, 64, v66
	v_and_b32_e32 v69, 31, v0
	v_ashrrev_i32_e32 v66, 1, v66
	v_lshrrev_b32_e32 v0, 3, v0
	v_and_b32_e32 v66, 0xffffffc0, v66
	v_and_or_b32 v0, v0, 4, s24
	v_add_u32_e32 v68, v0, v66
	v_or3_b32 v66, v69, v67, s23
	v_cvt_f16_f32_e32 v0, v50
	v_ashrrev_i32_e32 v67, 31, v66
	v_ashrrev_i32_e32 v69, 31, v68
	v_lshl_add_u64 v[66:67], v[66:67], 1, s[6:7]
	v_lshlrev_b64 v[100:101], 11, v[68:69]
	v_lshl_add_u64 v[100:101], v[66:67], 0, v[100:101]
	v_or_b32_e32 v70, 1, v68
	v_or_b32_e32 v72, 2, v68
	v_cvt_f16_f32_e32 v69, v51
	global_store_short v[100:101], v0, off
	v_cvt_f16_f32_e32 v0, v52
	v_ashrrev_i32_e32 v71, 31, v70
	v_ashrrev_i32_e32 v73, 31, v72
	v_lshlrev_b64 v[50:51], 11, v[70:71]
	v_lshlrev_b64 v[70:71], 11, v[72:73]
	v_lshl_add_u64 v[50:51], v[66:67], 0, v[50:51]
	v_lshl_add_u64 v[70:71], v[66:67], 0, v[70:71]
	v_or_b32_e32 v74, 3, v68
	v_or_b32_e32 v76, 8, v68
	global_store_short v[50:51], v69, off
	v_cvt_f16_f32_e32 v69, v53
	global_store_short v[70:71], v0, off
	v_cvt_f16_f32_e32 v0, v54
	v_ashrrev_i32_e32 v75, 31, v74
	v_ashrrev_i32_e32 v77, 31, v76
	v_lshlrev_b64 v[52:53], 11, v[74:75]
	v_lshlrev_b64 v[72:73], 11, v[76:77]
	v_lshl_add_u64 v[52:53], v[66:67], 0, v[52:53]
	v_lshl_add_u64 v[72:73], v[66:67], 0, v[72:73]
	v_or_b32_e32 v78, 9, v68
	v_or_b32_e32 v80, 10, v68
	global_store_short v[52:53], v69, off
	v_cvt_f16_f32_e32 v69, v55
	global_store_short v[72:73], v0, off
	v_cvt_f16_f32_e32 v0, v56
	v_ashrrev_i32_e32 v79, 31, v78
	v_ashrrev_i32_e32 v81, 31, v80
	v_lshlrev_b64 v[54:55], 11, v[78:79]
	v_lshlrev_b64 v[74:75], 11, v[80:81]
	v_lshl_add_u64 v[54:55], v[66:67], 0, v[54:55]
	v_lshl_add_u64 v[74:75], v[66:67], 0, v[74:75]
	v_or_b32_e32 v82, 11, v68
	v_or_b32_e32 v84, 16, v68
	global_store_short v[54:55], v69, off
	v_cvt_f16_f32_e32 v69, v57
	global_store_short v[74:75], v0, off
	v_cvt_f16_f32_e32 v0, v58
	v_ashrrev_i32_e32 v83, 31, v82
	v_ashrrev_i32_e32 v85, 31, v84
	v_lshlrev_b64 v[56:57], 11, v[82:83]
	v_lshlrev_b64 v[76:77], 11, v[84:85]
	v_lshl_add_u64 v[56:57], v[66:67], 0, v[56:57]
	v_lshl_add_u64 v[76:77], v[66:67], 0, v[76:77]
	v_or_b32_e32 v86, 17, v68
	v_or_b32_e32 v88, 18, v68
	global_store_short v[56:57], v69, off
	v_cvt_f16_f32_e32 v69, v59
	global_store_short v[76:77], v0, off
	v_cvt_f16_f32_e32 v0, v60
	v_ashrrev_i32_e32 v87, 31, v86
	v_ashrrev_i32_e32 v89, 31, v88
	v_lshlrev_b64 v[58:59], 11, v[86:87]
	v_lshlrev_b64 v[78:79], 11, v[88:89]
	v_lshl_add_u64 v[58:59], v[66:67], 0, v[58:59]
	v_lshl_add_u64 v[78:79], v[66:67], 0, v[78:79]
	v_or_b32_e32 v90, 19, v68
	v_or_b32_e32 v92, 24, v68
	global_store_short v[58:59], v69, off
	v_cvt_f16_f32_e32 v69, v61
	global_store_short v[78:79], v0, off
	v_cvt_f16_f32_e32 v0, v62
	v_ashrrev_i32_e32 v91, 31, v90
	v_ashrrev_i32_e32 v93, 31, v92
	v_lshlrev_b64 v[60:61], 11, v[90:91]
	v_lshlrev_b64 v[80:81], 11, v[92:93]
	v_lshl_add_u64 v[60:61], v[66:67], 0, v[60:61]
	v_lshl_add_u64 v[80:81], v[66:67], 0, v[80:81]
	v_or_b32_e32 v94, 25, v68
	v_or_b32_e32 v96, 26, v68
	global_store_short v[60:61], v69, off
	v_cvt_f16_f32_e32 v69, v63
	global_store_short v[80:81], v0, off
	v_cvt_f16_f32_e32 v0, v64
	v_ashrrev_i32_e32 v95, 31, v94
	v_ashrrev_i32_e32 v97, 31, v96
	v_lshlrev_b64 v[62:63], 11, v[94:95]
	v_lshlrev_b64 v[82:83], 11, v[96:97]
	v_lshl_add_u64 v[62:63], v[66:67], 0, v[62:63]
	v_lshl_add_u64 v[82:83], v[66:67], 0, v[82:83]
	v_or_b32_e32 v98, 27, v68
	global_store_short v[62:63], v69, off
	v_cvt_f16_f32_e32 v69, v65
	global_store_short v[82:83], v0, off
	v_cvt_f16_f32_e32 v0, v34
	v_ashrrev_i32_e32 v99, 31, v98
	v_cvt_f16_f32_e32 v34, v35
	v_lshlrev_b64 v[64:65], 11, v[98:99]
	v_cvt_f16_f32_e32 v35, v36
	v_lshl_add_u64 v[64:65], v[66:67], 0, v[64:65]
	v_cvt_f16_f32_e32 v36, v37
	global_store_short v[64:65], v69, off
	global_store_short v[100:101], v0, off offset:64
	global_store_short v[50:51], v34, off offset:64
	global_store_short v[70:71], v35, off offset:64
	global_store_short v[52:53], v36, off offset:64
	v_cvt_f16_f32_e32 v0, v38
	v_cvt_f16_f32_e32 v34, v39
	v_cvt_f16_f32_e32 v35, v40
	v_cvt_f16_f32_e32 v36, v41
	global_store_short v[72:73], v0, off offset:64
	global_store_short v[54:55], v34, off offset:64
	global_store_short v[74:75], v35, off offset:64
	global_store_short v[56:57], v36, off offset:64
	v_cvt_f16_f32_e32 v0, v42
	v_cvt_f16_f32_e32 v34, v43
	v_cvt_f16_f32_e32 v35, v44
	v_cvt_f16_f32_e32 v36, v45
	global_store_short v[76:77], v0, off offset:64
	global_store_short v[58:59], v34, off offset:64
	global_store_short v[78:79], v35, off offset:64
	global_store_short v[60:61], v36, off offset:64
	v_cvt_f16_f32_e32 v0, v46
	v_cvt_f16_f32_e32 v34, v47
	v_cvt_f16_f32_e32 v35, v48
	v_cvt_f16_f32_e32 v36, v49
; DI int TIDX() { int t = threadIdx.x; asm volatile("" : "+v"(t)); return t; }
; template <class F>
; DI void epi_foreach(f32x16 (&acc)[2][2], int m0, int n0, F f) {
;   const int lane = TIDX() & 63, w = TIDX() >> 6, wm = w >> 1, wn = w & 1, hh = lane >> 5, c = lane & 31;
; #pragma unroll
;   for (int mi = 0; mi < 2; ++mi)
; #pragma unroll
;     for (int ni = 0; ni < 2; ++ni) f(m0 + wm * 64 + mi * 32 + 4 * hh, n0 + wn * 64 + ni * 32 + c, acc[mi][ni]);
; }
; DI void phase_gemm_plain(const h16* A, int lda, const h16* Bt, int K, h16* C, int ldc, int mt0, int mt1, int ntn, char* smem) {
;     ...
;     epi_foreach(acc, m0, n0, [&](int rbase, int n, const f32x16& v) {
; #pragma unroll
;       for (int i = 0; i < 16; ++i) C[(size_t)EROW(rbase, i) * ldc + n] = (h16)v[i];
;     });
	global_store_short v[80:81], v0, off offset:64
	global_store_short v[62:63], v34, off offset:64
	global_store_short v[82:83], v35, off offset:64
	global_store_short v[64:65], v36, off offset:64
	v_or_b32_e32 v34, 32, v68
	v_cvt_f16_f32_e32 v0, v18
	v_ashrrev_i32_e32 v35, 31, v34
	v_lshlrev_b64 v[34:35], 11, v[34:35]
	v_lshl_add_u64 v[34:35], v[66:67], 0, v[34:35]
	v_or_b32_e32 v36, 33, v68
	global_store_short v[34:35], v0, off
	v_cvt_f16_f32_e32 v0, v19
	v_ashrrev_i32_e32 v37, 31, v36
	v_or_b32_e32 v38, 34, v68
	v_lshlrev_b64 v[18:19], 11, v[36:37]
	v_ashrrev_i32_e32 v39, 31, v38
	v_lshl_add_u64 v[18:19], v[66:67], 0, v[18:19]
	v_or_b32_e32 v40, 35, v68
	global_store_short v[18:19], v0, off
	v_lshlrev_b64 v[36:37], 11, v[38:39]
	v_cvt_f16_f32_e32 v0, v21
	v_ashrrev_i32_e32 v41, 31, v40
	v_lshl_add_u64 v[36:37], v[66:67], 0, v[36:37]
	v_or_b32_e32 v42, 40, v68
	global_store_short v[36:37], v20, off
	v_lshlrev_b64 v[20:21], 11, v[40:41]
	v_cvt_f16_f32_e32 v22, v22
	v_ashrrev_i32_e32 v43, 31, v42
	v_lshl_add_u64 v[20:21], v[66:67], 0, v[20:21]
	v_or_b32_e32 v44, 41, v68
	global_store_short v[20:21], v0, off
	v_lshlrev_b64 v[38:39], 11, v[42:43]
	v_cvt_f16_f32_e32 v0, v23
	v_ashrrev_i32_e32 v45, 31, v44
	v_lshl_add_u64 v[38:39], v[66:67], 0, v[38:39]
	v_or_b32_e32 v46, 42, v68
	global_store_short v[38:39], v22, off
	v_lshlrev_b64 v[22:23], 11, v[44:45]
	v_cvt_f16_f32_e32 v24, v24
	v_ashrrev_i32_e32 v47, 31, v46
	v_lshl_add_u64 v[22:23], v[66:67], 0, v[22:23]
	v_or_b32_e32 v48, 43, v68
	global_store_short v[22:23], v0, off
	v_lshlrev_b64 v[40:41], 11, v[46:47]
	v_cvt_f16_f32_e32 v0, v25
	v_ashrrev_i32_e32 v49, 31, v48
	v_lshl_add_u64 v[40:41], v[66:67], 0, v[40:41]
	v_or_b32_e32 v50, 48, v68
	global_store_short v[40:41], v24, off
	v_lshlrev_b64 v[24:25], 11, v[48:49]
	v_cvt_f16_f32_e32 v26, v26
	v_ashrrev_i32_e32 v51, 31, v50
	v_lshl_add_u64 v[24:25], v[66:67], 0, v[24:25]
	v_or_b32_e32 v52, 49, v68
	global_store_short v[24:25], v0, off
	v_lshlrev_b64 v[42:43], 11, v[50:51]
	v_cvt_f16_f32_e32 v0, v27
	v_ashrrev_i32_e32 v53, 31, v52
	v_lshl_add_u64 v[42:43], v[66:67], 0, v[42:43]
	v_or_b32_e32 v54, 50, v68
	global_store_short v[42:43], v26, off
	v_lshlrev_b64 v[26:27], 11, v[52:53]
	v_cvt_f16_f32_e32 v28, v28
	v_ashrrev_i32_e32 v55, 31, v54
	v_lshl_add_u64 v[26:27], v[66:67], 0, v[26:27]
	v_or_b32_e32 v56, 51, v68
	global_store_short v[26:27], v0, off
	v_lshlrev_b64 v[44:45], 11, v[54:55]
	v_cvt_f16_f32_e32 v0, v29
	v_ashrrev_i32_e32 v57, 31, v56
	v_lshl_add_u64 v[44:45], v[66:67], 0, v[44:45]
	v_or_b32_e32 v58, 56, v68
	global_store_short v[44:45], v28, off
	v_lshlrev_b64 v[28:29], 11, v[56:57]
	v_cvt_f16_f32_e32 v30, v30
	v_ashrrev_i32_e32 v59, 31, v58
	v_lshl_add_u64 v[28:29], v[66:67], 0, v[28:29]
	v_or_b32_e32 v60, 57, v68
	global_store_short v[28:29], v0, off
	v_lshlrev_b64 v[46:47], 11, v[58:59]
	v_cvt_f16_f32_e32 v0, v31
	v_ashrrev_i32_e32 v61, 31, v60
	v_lshl_add_u64 v[46:47], v[66:67], 0, v[46:47]
	v_or_b32_e32 v62, 58, v68
	global_store_short v[46:47], v30, off
	v_lshlrev_b64 v[30:31], 11, v[60:61]
	v_cvt_f16_f32_e32 v32, v32
	v_ashrrev_i32_e32 v63, 31, v62
	v_lshl_add_u64 v[30:31], v[66:67], 0, v[30:31]
	v_or_b32_e32 v64, 59, v68
	global_store_short v[30:31], v0, off
	v_lshlrev_b64 v[48:49], 11, v[62:63]
	v_cvt_f16_f32_e32 v0, v33
	v_ashrrev_i32_e32 v65, 31, v64
	v_lshl_add_u64 v[48:49], v[66:67], 0, v[48:49]
	global_store_short v[48:49], v32, off
	v_lshlrev_b64 v[32:33], 11, v[64:65]
	v_lshl_add_u64 v[32:33], v[66:67], 0, v[32:33]
	v_cvt_f16_f32_e32 v2, v2
	global_store_short v[32:33], v0, off
	v_cvt_f16_f32_e32 v0, v4
	v_cvt_f16_f32_e32 v3, v3
	global_store_short v[34:35], v2, off offset:64
	global_store_short v[18:19], v3, off offset:64
	v_cvt_f16_f32_e32 v2, v5
	global_store_short v[36:37], v0, off offset:64
	v_cvt_f16_f32_e32 v0, v6
	v_cvt_f16_f32_e32 v3, v7
	global_store_short v[20:21], v2, off offset:64
	v_cvt_f16_f32_e32 v2, v8
	global_store_short v[38:39], v0, off offset:64
	global_store_short v[22:23], v3, off offset:64
	v_cvt_f16_f32_e32 v0, v9
	v_cvt_f16_f32_e32 v3, v11
	global_store_short v[40:41], v2, off offset:64
	v_cvt_f16_f32_e32 v2, v10
	global_store_short v[24:25], v0, off offset:64
	v_cvt_f16_f32_e32 v0, v12
	global_store_short v[42:43], v2, off offset:64
	global_store_short v[26:27], v3, off offset:64
	v_cvt_f16_f32_e32 v2, v13
	global_store_short v[44:45], v0, off offset:64
	v_cvt_f16_f32_e32 v0, v14
	v_cvt_f16_f32_e32 v3, v15
	global_store_short v[28:29], v2, off offset:64
	v_cvt_f16_f32_e32 v2, v16
	global_store_short v[46:47], v0, off offset:64
	global_store_short v[30:31], v3, off offset:64
	v_cvt_f16_f32_e32 v0, v17
	v_readlane_b32 s2, v252, 63
	s_add_i32 s15, s15, s2
	s_cmp_ge_i32 s15, s14
	global_store_short v[48:49], v2, off offset:64
	global_store_short v[32:33], v0, off offset:64
	s_cbranch_scc1 .LBB0_64

; DI int TIDX() { int t = threadIdx.x; asm volatile("" : "+v"(t)); return t; }
; DI float sigmoidf_(float x) { return __builtin_amdgcn_rcpf(1.f + __expf(-x)); }
; DI void phase_ffn1(const P& p, int l, int hf, char* smem) {
;     ...
;     const int lane = TIDX() & 63, w = TIDX() >> 6, wm = w >> 1, wn = w & 1, hh = lane >> 5, c = lane & 31;
;     const int ml0 = m0 - mt0 * 128;
; #pragma unroll
;     for (int mi = 0; mi < 4; ++mi) {
;       const int rbase = ml0 + wm * 128 + mi * 32 + 4 * hh, n = c0 + wn * 32 + c;
; #pragma unroll
;       for (int i = 0; i < 16; ++i) {
;         const float g = acc[mi][0][i];
;         act[(size_t)EROW(rbase, i) * 2816 + n] = (h16)(g * sigmoidf_(g) * acc[mi][1][i]);
;       }
;     }
.LBB0_69:
	v_mov_b32_e32 v0, v203
	v_mov_b32_e32 v130, v203
	s_nop 7
	s_nop 7
	s_nop 7
	s_movk_i32 s2, 0x1600
	v_and_b32_e32 v132, 0xffffff80, v203
	v_add_u32_e32 v132, s12, v132
	v_lshrrev_b32_e32 v133, 3, v203
	v_and_or_b32 v132, v133, 4, v132
	v_and_b32_e32 v131, 31, v203
	v_lshrrev_b32_e32 v130, 1, v203
	v_and_b32_e32 v130, 32, v130
	v_or3_b32 v130, v131, v130, s26
	v_lshlrev_b32_e32 v130, 1, v130
	v_mad_u32_u24 v130, v132, s2, v130
	v_mul_f32_e32 v178, 0xbfb8aa3b, v114
	v_mul_f32_e32 v179, 0xbfb8aa3b, v115
	v_mul_f32_e32 v180, 0xbfb8aa3b, v116
	v_mul_f32_e32 v181, 0xbfb8aa3b, v117
	v_mul_f32_e32 v182, 0xbfb8aa3b, v118
	v_mul_f32_e32 v183, 0xbfb8aa3b, v119
	v_mul_f32_e32 v184, 0xbfb8aa3b, v120
	v_mul_f32_e32 v185, 0xbfb8aa3b, v121
	v_exp_f32_e32 v178, v178
	v_exp_f32_e32 v179, v179
	v_exp_f32_e32 v180, v180
	v_exp_f32_e32 v181, v181
	v_exp_f32_e32 v182, v182
	v_exp_f32_e32 v183, v183
	v_exp_f32_e32 v184, v184
	v_exp_f32_e32 v185, v185
	v_mov_b32_e32 v186, v130
	v_add_u32_e32 v187, 0x1600, v130
	v_add_u32_e32 v188, 0x2c00, v130
	v_add_u32_e32 v189, 0x4200, v130
	v_add_u32_e32 v190, 0xb000, v130
	v_add_u32_e32 v191, 0xc600, v130
	v_add_u32_e32 v192, 0xdc00, v130
	v_add_u32_e32 v193, 0xf200, v130
	v_add_f32_e32 v178, 1.0, v178
	v_add_f32_e32 v179, 1.0, v179
	v_add_f32_e32 v180, 1.0, v180
	v_add_f32_e32 v181, 1.0, v181
	v_add_f32_e32 v182, 1.0, v182
	v_add_f32_e32 v183, 1.0, v183
	v_add_f32_e32 v184, 1.0, v184
	v_add_f32_e32 v185, 1.0, v185
	v_rcp_f32_e32 v178, v178
	v_rcp_f32_e32 v179, v179
	v_rcp_f32_e32 v180, v180
	v_rcp_f32_e32 v181, v181
	v_rcp_f32_e32 v182, v182
	v_rcp_f32_e32 v183, v183
	v_rcp_f32_e32 v184, v184
	v_rcp_f32_e32 v185, v185
	v_mul_f32_e32 v178, v114, v178
	v_mul_f32_e32 v179, v115, v179
	v_mul_f32_e32 v180, v116, v180
	v_mul_f32_e32 v181, v117, v181
	v_mul_f32_e32 v182, v118, v182
	v_mul_f32_e32 v183, v119, v183
	v_mul_f32_e32 v184, v120, v184
	v_mul_f32_e32 v185, v121, v185
	v_fma_mixlo_f16 v178, v98, v178, 0
	v_fma_mixlo_f16 v179, v99, v179, 0
	v_fma_mixlo_f16 v180, v100, v180, 0
	v_fma_mixlo_f16 v181, v101, v181, 0
	v_fma_mixlo_f16 v182, v102, v182, 0
	v_fma_mixlo_f16 v183, v103, v183, 0
	v_fma_mixlo_f16 v184, v104, v184, 0
	v_fma_mixlo_f16 v185, v105, v185, 0
	global_store_short v186, v178, s[8:9]
	global_store_short v187, v179, s[8:9]
	global_store_short v188, v180, s[8:9]
	global_store_short v189, v181, s[8:9]
	global_store_short v190, v182, s[8:9]
	global_store_short v191, v183, s[8:9]
	global_store_short v192, v184, s[8:9]
	global_store_short v193, v185, s[8:9]
	v_mul_f32_e32 v178, 0xbfb8aa3b, v122
	v_mul_f32_e32 v179, 0xbfb8aa3b, v123
	v_mul_f32_e32 v180, 0xbfb8aa3b, v124
	v_mul_f32_e32 v181, 0xbfb8aa3b, v125
	v_mul_f32_e32 v182, 0xbfb8aa3b, v126
	v_mul_f32_e32 v183, 0xbfb8aa3b, v127
	v_mul_f32_e32 v184, 0xbfb8aa3b, v128
	v_mul_f32_e32 v185, 0xbfb8aa3b, v129
	v_exp_f32_e32 v178, v178
	v_exp_f32_e32 v179, v179
	v_exp_f32_e32 v180, v180
	v_exp_f32_e32 v181, v181
	v_exp_f32_e32 v182, v182
	v_exp_f32_e32 v183, v183
	v_exp_f32_e32 v184, v184
	v_exp_f32_e32 v185, v185
	v_add_u32_e32 v186, 0x16000, v130
	v_add_u32_e32 v187, 0x17600, v130
	v_add_u32_e32 v188, 0x18c00, v130
	v_add_u32_e32 v189, 0x1a200, v130
	v_add_u32_e32 v190, 0x21000, v130
	v_add_u32_e32 v191, 0x22600, v130
	v_add_u32_e32 v192, 0x23c00, v130
	v_add_u32_e32 v193, 0x25200, v130
	v_add_f32_e32 v178, 1.0, v178
	v_add_f32_e32 v179, 1.0, v179
	v_add_f32_e32 v180, 1.0, v180
	v_add_f32_e32 v181, 1.0, v181
	v_add_f32_e32 v182, 1.0, v182
	v_add_f32_e32 v183, 1.0, v183
	v_add_f32_e32 v184, 1.0, v184
	v_add_f32_e32 v185, 1.0, v185
	v_rcp_f32_e32 v178, v178
	v_rcp_f32_e32 v179, v179
	v_rcp_f32_e32 v180, v180
	v_rcp_f32_e32 v181, v181
	v_rcp_f32_e32 v182, v182
	v_rcp_f32_e32 v183, v183
	v_rcp_f32_e32 v184, v184
	v_rcp_f32_e32 v185, v185
	v_mul_f32_e32 v178, v122, v178
	v_mul_f32_e32 v179, v123, v179
	v_mul_f32_e32 v180, v124, v180
	v_mul_f32_e32 v181, v125, v181
	v_mul_f32_e32 v182, v126, v182
	v_mul_f32_e32 v183, v127, v183
	v_mul_f32_e32 v184, v128, v184
	v_mul_f32_e32 v185, v129, v185
	v_fma_mixlo_f16 v178, v106, v178, 0
	v_fma_mixlo_f16 v179, v107, v179, 0
	v_fma_mixlo_f16 v180, v108, v180, 0
	v_fma_mixlo_f16 v181, v109, v181, 0
	v_fma_mixlo_f16 v182, v110, v182, 0
	v_fma_mixlo_f16 v183, v111, v183, 0
	v_fma_mixlo_f16 v184, v112, v184, 0
	v_fma_mixlo_f16 v185, v113, v185, 0
	global_store_short v186, v178, s[8:9]
	global_store_short v187, v179, s[8:9]
	global_store_short v188, v180, s[8:9]
	global_store_short v189, v181, s[8:9]
	global_store_short v190, v182, s[8:9]
	global_store_short v191, v183, s[8:9]
	global_store_short v192, v184, s[8:9]
	global_store_short v193, v185, s[8:9]
	v_mul_f32_e32 v178, 0xbfb8aa3b, v82
	v_mul_f32_e32 v179, 0xbfb8aa3b, v83
	v_mul_f32_e32 v180, 0xbfb8aa3b, v84
	v_mul_f32_e32 v181, 0xbfb8aa3b, v85
	v_mul_f32_e32 v182, 0xbfb8aa3b, v86
	v_mul_f32_e32 v183, 0xbfb8aa3b, v87
	v_mul_f32_e32 v184, 0xbfb8aa3b, v88
	v_mul_f32_e32 v185, 0xbfb8aa3b, v89
	v_exp_f32_e32 v178, v178
	v_exp_f32_e32 v179, v179
	v_exp_f32_e32 v180, v180
	v_exp_f32_e32 v181, v181
	v_exp_f32_e32 v182, v182
	v_exp_f32_e32 v183, v183
	v_exp_f32_e32 v184, v184
	v_exp_f32_e32 v185, v185
	v_add_u32_e32 v186, 0x2c000, v130
	v_add_u32_e32 v187, 0x2d600, v130
	v_add_u32_e32 v188, 0x2ec00, v130
	v_add_u32_e32 v189, 0x30200, v130
	v_add_u32_e32 v190, 0x37000, v130
	v_add_u32_e32 v191, 0x38600, v130
	v_add_u32_e32 v192, 0x39c00, v130
	v_add_u32_e32 v193, 0x3b200, v130
	v_add_f32_e32 v178, 1.0, v178
	v_add_f32_e32 v179, 1.0, v179
	v_add_f32_e32 v180, 1.0, v180
	v_add_f32_e32 v181, 1.0, v181
	v_add_f32_e32 v182, 1.0, v182
	v_add_f32_e32 v183, 1.0, v183
	v_add_f32_e32 v184, 1.0, v184
; DI int TIDX() { int t = threadIdx.x; asm volatile("" : "+v"(t)); return t; }
; DI float sigmoidf_(float x) { return __builtin_amdgcn_rcpf(1.f + __expf(-x)); }
; DI void phase_ffn1(const P& p, int l, int hf, char* smem) {
;     ...
;     const int lane = TIDX() & 63, w = TIDX() >> 6, wm = w >> 1, wn = w & 1, hh = lane >> 5, c = lane & 31;
;     const int ml0 = m0 - mt0 * 128;
; #pragma unroll
;     for (int mi = 0; mi < 4; ++mi) {
;       const int rbase = ml0 + wm * 128 + mi * 32 + 4 * hh, n = c0 + wn * 32 + c;
; #pragma unroll
;       for (int i = 0; i < 16; ++i) {
;         const float g = acc[mi][0][i];
;         act[(size_t)EROW(rbase, i) * 2816 + n] = (h16)(g * sigmoidf_(g) * acc[mi][1][i]);
;       }
;     }
	v_add_f32_e32 v185, 1.0, v185
	v_rcp_f32_e32 v178, v178
	v_rcp_f32_e32 v179, v179
	v_rcp_f32_e32 v180, v180
	v_rcp_f32_e32 v181, v181
	v_rcp_f32_e32 v182, v182
	v_rcp_f32_e32 v183, v183
	v_rcp_f32_e32 v184, v184
	v_rcp_f32_e32 v185, v185
	v_mul_f32_e32 v178, v82, v178
	v_mul_f32_e32 v179, v83, v179
	v_mul_f32_e32 v180, v84, v180
	v_mul_f32_e32 v181, v85, v181
	v_mul_f32_e32 v182, v86, v182
	v_mul_f32_e32 v183, v87, v183
	v_mul_f32_e32 v184, v88, v184
	v_mul_f32_e32 v185, v89, v185
	v_fma_mixlo_f16 v178, v66, v178, 0
	v_fma_mixlo_f16 v179, v67, v179, 0
	v_fma_mixlo_f16 v180, v68, v180, 0
	v_fma_mixlo_f16 v181, v69, v181, 0
	v_fma_mixlo_f16 v182, v70, v182, 0
	v_fma_mixlo_f16 v183, v71, v183, 0
	v_fma_mixlo_f16 v184, v72, v184, 0
	v_fma_mixlo_f16 v185, v73, v185, 0
	global_store_short v186, v178, s[8:9]
	global_store_short v187, v179, s[8:9]
	global_store_short v188, v180, s[8:9]
	global_store_short v189, v181, s[8:9]
	global_store_short v190, v182, s[8:9]
	global_store_short v191, v183, s[8:9]
	global_store_short v192, v184, s[8:9]
	global_store_short v193, v185, s[8:9]
	v_mul_f32_e32 v178, 0xbfb8aa3b, v90
	v_mul_f32_e32 v179, 0xbfb8aa3b, v91
	v_mul_f32_e32 v180, 0xbfb8aa3b, v92
	v_mul_f32_e32 v181, 0xbfb8aa3b, v93
	v_mul_f32_e32 v182, 0xbfb8aa3b, v94
	v_mul_f32_e32 v183, 0xbfb8aa3b, v95
	v_mul_f32_e32 v184, 0xbfb8aa3b, v96
	v_mul_f32_e32 v185, 0xbfb8aa3b, v97
	v_exp_f32_e32 v178, v178
	v_exp_f32_e32 v179, v179
	v_exp_f32_e32 v180, v180
	v_exp_f32_e32 v181, v181
	v_exp_f32_e32 v182, v182
	v_exp_f32_e32 v183, v183
	v_exp_f32_e32 v184, v184
	v_exp_f32_e32 v185, v185
	v_add_u32_e32 v186, 0x42000, v130
	v_add_u32_e32 v187, 0x43600, v130
	v_add_u32_e32 v188, 0x44c00, v130
	v_add_u32_e32 v189, 0x46200, v130
	v_add_u32_e32 v190, 0x4d000, v130
	v_add_u32_e32 v191, 0x4e600, v130
	v_add_u32_e32 v192, 0x4fc00, v130
	v_add_u32_e32 v193, 0x51200, v130
	v_add_f32_e32 v178, 1.0, v178
	v_add_f32_e32 v179, 1.0, v179
	v_add_f32_e32 v180, 1.0, v180
	v_add_f32_e32 v181, 1.0, v181
	v_add_f32_e32 v182, 1.0, v182
	v_add_f32_e32 v183, 1.0, v183
	v_add_f32_e32 v184, 1.0, v184
	v_add_f32_e32 v185, 1.0, v185
	v_rcp_f32_e32 v178, v178
	v_rcp_f32_e32 v179, v179
	v_rcp_f32_e32 v180, v180
	v_rcp_f32_e32 v181, v181
	v_rcp_f32_e32 v182, v182
	v_rcp_f32_e32 v183, v183
	v_rcp_f32_e32 v184, v184
	v_rcp_f32_e32 v185, v185
	v_mul_f32_e32 v178, v90, v178
	v_mul_f32_e32 v179, v91, v179
	v_mul_f32_e32 v180, v92, v180
	v_mul_f32_e32 v181, v93, v181
	v_mul_f32_e32 v182, v94, v182
	v_mul_f32_e32 v183, v95, v183
	v_mul_f32_e32 v184, v96, v184
	v_mul_f32_e32 v185, v97, v185
	v_fma_mixlo_f16 v178, v74, v178, 0
	v_fma_mixlo_f16 v179, v75, v179, 0
	v_fma_mixlo_f16 v180, v76, v180, 0
	v_fma_mixlo_f16 v181, v77, v181, 0
	v_fma_mixlo_f16 v182, v78, v182, 0
	v_fma_mixlo_f16 v183, v79, v183, 0
	v_fma_mixlo_f16 v184, v80, v184, 0
	v_fma_mixlo_f16 v185, v81, v185, 0
	global_store_short v186, v178, s[8:9]
	global_store_short v187, v179, s[8:9]
	global_store_short v188, v180, s[8:9]
	global_store_short v189, v181, s[8:9]
	global_store_short v190, v182, s[8:9]
	global_store_short v191, v183, s[8:9]
	global_store_short v192, v184, s[8:9]
	global_store_short v193, v185, s[8:9]
	v_mul_f32_e32 v178, 0xbfb8aa3b, v50
	v_mul_f32_e32 v179, 0xbfb8aa3b, v51
	v_mul_f32_e32 v180, 0xbfb8aa3b, v52
	v_mul_f32_e32 v181, 0xbfb8aa3b, v53
	v_mul_f32_e32 v182, 0xbfb8aa3b, v54
	v_mul_f32_e32 v183, 0xbfb8aa3b, v55
	v_mul_f32_e32 v184, 0xbfb8aa3b, v56
	v_mul_f32_e32 v185, 0xbfb8aa3b, v57
	v_exp_f32_e32 v178, v178
	v_exp_f32_e32 v179, v179
	v_exp_f32_e32 v180, v180
	v_exp_f32_e32 v181, v181
	v_exp_f32_e32 v182, v182
	v_exp_f32_e32 v183, v183
	v_exp_f32_e32 v184, v184
	v_exp_f32_e32 v185, v185
	v_add_u32_e32 v186, 0x58000, v130
	v_add_u32_e32 v187, 0x59600, v130
	v_add_u32_e32 v188, 0x5ac00, v130
	v_add_u32_e32 v189, 0x5c200, v130
	v_add_u32_e32 v190, 0x63000, v130
	v_add_u32_e32 v191, 0x64600, v130
	v_add_u32_e32 v192, 0x65c00, v130
	v_add_u32_e32 v193, 0x67200, v130
	v_add_f32_e32 v178, 1.0, v178
	v_add_f32_e32 v179, 1.0, v179
	v_add_f32_e32 v180, 1.0, v180
	v_add_f32_e32 v181, 1.0, v181
	v_add_f32_e32 v182, 1.0, v182
	v_add_f32_e32 v183, 1.0, v183
	v_add_f32_e32 v184, 1.0, v184
	v_add_f32_e32 v185, 1.0, v185
	v_rcp_f32_e32 v178, v178
	v_rcp_f32_e32 v179, v179
	v_rcp_f32_e32 v180, v180
	v_rcp_f32_e32 v181, v181
	v_rcp_f32_e32 v182, v182
	v_rcp_f32_e32 v183, v183
	v_rcp_f32_e32 v184, v184
	v_rcp_f32_e32 v185, v185
	v_mul_f32_e32 v178, v50, v178
	v_mul_f32_e32 v179, v51, v179
	v_mul_f32_e32 v180, v52, v180
	v_mul_f32_e32 v181, v53, v181
	v_mul_f32_e32 v182, v54, v182
	v_mul_f32_e32 v183, v55, v183
	v_mul_f32_e32 v184, v56, v184
	v_mul_f32_e32 v185, v57, v185
	v_fma_mixlo_f16 v178, v34, v178, 0
	v_fma_mixlo_f16 v179, v35, v179, 0
	v_fma_mixlo_f16 v180, v36, v180, 0
	v_fma_mixlo_f16 v181, v37, v181, 0
	v_fma_mixlo_f16 v182, v38, v182, 0
	v_fma_mixlo_f16 v183, v39, v183, 0
	v_fma_mixlo_f16 v184, v40, v184, 0
	v_fma_mixlo_f16 v185, v41, v185, 0
	global_store_short v186, v178, s[8:9]
	global_store_short v187, v179, s[8:9]
	global_store_short v188, v180, s[8:9]
	global_store_short v189, v181, s[8:9]
	global_store_short v190, v182, s[8:9]
	global_store_short v191, v183, s[8:9]
	global_store_short v192, v184, s[8:9]
	global_store_short v193, v185, s[8:9]
	v_mul_f32_e32 v178, 0xbfb8aa3b, v58
	v_mul_f32_e32 v179, 0xbfb8aa3b, v59
	v_mul_f32_e32 v180, 0xbfb8aa3b, v60
	v_mul_f32_e32 v181, 0xbfb8aa3b, v61
	v_mul_f32_e32 v182, 0xbfb8aa3b, v62
	v_mul_f32_e32 v183, 0xbfb8aa3b, v63
	v_mul_f32_e32 v184, 0xbfb8aa3b, v64
	v_mul_f32_e32 v185, 0xbfb8aa3b, v65
	v_exp_f32_e32 v178, v178
	v_exp_f32_e32 v179, v179
	v_exp_f32_e32 v180, v180
; DI int TIDX() { int t = threadIdx.x; asm volatile("" : "+v"(t)); return t; }
; DI float sigmoidf_(float x) { return __builtin_amdgcn_rcpf(1.f + __expf(-x)); }
; DI void phase_ffn1(const P& p, int l, int hf, char* smem) {
;     ...
;     const int lane = TIDX() & 63, w = TIDX() >> 6, wm = w >> 1, wn = w & 1, hh = lane >> 5, c = lane & 31;
;     const int ml0 = m0 - mt0 * 128;
; #pragma unroll
;     for (int mi = 0; mi < 4; ++mi) {
;       const int rbase = ml0 + wm * 128 + mi * 32 + 4 * hh, n = c0 + wn * 32 + c;
; #pragma unroll
;       for (int i = 0; i < 16; ++i) {
;         const float g = acc[mi][0][i];
;         act[(size_t)EROW(rbase, i) * 2816 + n] = (h16)(g * sigmoidf_(g) * acc[mi][1][i]);
;       }
;     }
	v_exp_f32_e32 v181, v181
	v_exp_f32_e32 v182, v182
	v_exp_f32_e32 v183, v183
	v_exp_f32_e32 v184, v184
	v_exp_f32_e32 v185, v185
	v_add_u32_e32 v186, 0x6e000, v130
	v_add_u32_e32 v187, 0x6f600, v130
	v_add_u32_e32 v188, 0x70c00, v130
	v_add_u32_e32 v189, 0x72200, v130
	v_add_u32_e32 v190, 0x79000, v130
	v_add_u32_e32 v191, 0x7a600, v130
	v_add_u32_e32 v192, 0x7bc00, v130
	v_add_u32_e32 v193, 0x7d200, v130
	v_add_f32_e32 v178, 1.0, v178
	v_add_f32_e32 v179, 1.0, v179
	v_add_f32_e32 v180, 1.0, v180
	v_add_f32_e32 v181, 1.0, v181
	v_add_f32_e32 v182, 1.0, v182
	v_add_f32_e32 v183, 1.0, v183
	v_add_f32_e32 v184, 1.0, v184
	v_add_f32_e32 v185, 1.0, v185
	v_rcp_f32_e32 v178, v178
	v_rcp_f32_e32 v179, v179
	v_rcp_f32_e32 v180, v180
	v_rcp_f32_e32 v181, v181
	v_rcp_f32_e32 v182, v182
	v_rcp_f32_e32 v183, v183
	v_rcp_f32_e32 v184, v184
	v_rcp_f32_e32 v185, v185
	v_mul_f32_e32 v178, v58, v178
	v_mul_f32_e32 v179, v59, v179
	v_mul_f32_e32 v180, v60, v180
	v_mul_f32_e32 v181, v61, v181
	v_mul_f32_e32 v182, v62, v182
	v_mul_f32_e32 v183, v63, v183
	v_mul_f32_e32 v184, v64, v184
	v_mul_f32_e32 v185, v65, v185
	v_fma_mixlo_f16 v178, v42, v178, 0
	v_fma_mixlo_f16 v179, v43, v179, 0
	v_fma_mixlo_f16 v180, v44, v180, 0
	v_fma_mixlo_f16 v181, v45, v181, 0
	v_fma_mixlo_f16 v182, v46, v182, 0
	v_fma_mixlo_f16 v183, v47, v183, 0
	v_fma_mixlo_f16 v184, v48, v184, 0
	v_fma_mixlo_f16 v185, v49, v185, 0
	global_store_short v186, v178, s[8:9]
	global_store_short v187, v179, s[8:9]
	global_store_short v188, v180, s[8:9]
	global_store_short v189, v181, s[8:9]
	global_store_short v190, v182, s[8:9]
	global_store_short v191, v183, s[8:9]
	global_store_short v192, v184, s[8:9]
	global_store_short v193, v185, s[8:9]
	v_mul_f32_e32 v178, 0xbfb8aa3b, v18
	v_mul_f32_e32 v179, 0xbfb8aa3b, v19
	v_mul_f32_e32 v180, 0xbfb8aa3b, v20
	v_mul_f32_e32 v181, 0xbfb8aa3b, v21
	v_mul_f32_e32 v182, 0xbfb8aa3b, v22
	v_mul_f32_e32 v183, 0xbfb8aa3b, v23
	v_mul_f32_e32 v184, 0xbfb8aa3b, v24
	v_mul_f32_e32 v185, 0xbfb8aa3b, v25
	v_exp_f32_e32 v178, v178
	v_exp_f32_e32 v179, v179
	v_exp_f32_e32 v180, v180
	v_exp_f32_e32 v181, v181
	v_exp_f32_e32 v182, v182
	v_exp_f32_e32 v183, v183
	v_exp_f32_e32 v184, v184
	v_exp_f32_e32 v185, v185
	v_add_u32_e32 v186, 0x84000, v130
	v_add_u32_e32 v187, 0x85600, v130
	v_add_u32_e32 v188, 0x86c00, v130
	v_add_u32_e32 v189, 0x88200, v130
	v_add_u32_e32 v190, 0x8f000, v130
	v_add_u32_e32 v191, 0x90600, v130
	v_add_u32_e32 v192, 0x91c00, v130
	v_add_u32_e32 v193, 0x93200, v130
	v_add_f32_e32 v178, 1.0, v178
	v_add_f32_e32 v179, 1.0, v179
	v_add_f32_e32 v180, 1.0, v180
	v_add_f32_e32 v181, 1.0, v181
	v_add_f32_e32 v182, 1.0, v182
	v_add_f32_e32 v183, 1.0, v183
	v_add_f32_e32 v184, 1.0, v184
	v_add_f32_e32 v185, 1.0, v185
	v_rcp_f32_e32 v178, v178
	v_rcp_f32_e32 v179, v179
	v_rcp_f32_e32 v180, v180
	v_rcp_f32_e32 v181, v181
	v_rcp_f32_e32 v182, v182
	v_rcp_f32_e32 v183, v183
	v_rcp_f32_e32 v184, v184
	v_rcp_f32_e32 v185, v185
	v_mul_f32_e32 v178, v18, v178
	v_mul_f32_e32 v179, v19, v179
	v_mul_f32_e32 v180, v20, v180
	v_mul_f32_e32 v181, v21, v181
	v_mul_f32_e32 v182, v22, v182
	v_mul_f32_e32 v183, v23, v183
	v_mul_f32_e32 v184, v24, v184
	v_mul_f32_e32 v185, v25, v185
	v_fma_mixlo_f16 v178, v2, v178, 0
	v_fma_mixlo_f16 v179, v3, v179, 0
	v_fma_mixlo_f16 v180, v4, v180, 0
	v_fma_mixlo_f16 v181, v5, v181, 0
	v_fma_mixlo_f16 v182, v6, v182, 0
	v_fma_mixlo_f16 v183, v7, v183, 0
	v_fma_mixlo_f16 v184, v8, v184, 0
	v_fma_mixlo_f16 v185, v9, v185, 0
	global_store_short v186, v178, s[8:9]
	global_store_short v187, v179, s[8:9]
	global_store_short v188, v180, s[8:9]
	global_store_short v189, v181, s[8:9]
	global_store_short v190, v182, s[8:9]
	global_store_short v191, v183, s[8:9]
	global_store_short v192, v184, s[8:9]
	global_store_short v193, v185, s[8:9]
	v_mul_f32_e32 v178, 0xbfb8aa3b, v26
	v_mul_f32_e32 v179, 0xbfb8aa3b, v27
	v_mul_f32_e32 v180, 0xbfb8aa3b, v28
	v_mul_f32_e32 v181, 0xbfb8aa3b, v29
	v_mul_f32_e32 v182, 0xbfb8aa3b, v30
	v_mul_f32_e32 v183, 0xbfb8aa3b, v31
	v_mul_f32_e32 v184, 0xbfb8aa3b, v32
	v_mul_f32_e32 v185, 0xbfb8aa3b, v33
	v_exp_f32_e32 v178, v178
	v_exp_f32_e32 v179, v179
	v_exp_f32_e32 v180, v180
	v_exp_f32_e32 v181, v181
	v_exp_f32_e32 v182, v182
	v_exp_f32_e32 v183, v183
	v_exp_f32_e32 v184, v184
	v_exp_f32_e32 v185, v185
	v_add_u32_e32 v186, 0x9a000, v130
	v_add_u32_e32 v187, 0x9b600, v130
	v_add_u32_e32 v188, 0x9cc00, v130
	v_add_u32_e32 v189, 0x9e200, v130
	v_add_u32_e32 v190, 0xa5000, v130
	v_add_u32_e32 v191, 0xa6600, v130
	v_add_u32_e32 v192, 0xa7c00, v130
	v_add_u32_e32 v193, 0xa9200, v130
	v_add_f32_e32 v178, 1.0, v178
	v_add_f32_e32 v179, 1.0, v179
	v_add_f32_e32 v180, 1.0, v180
	v_add_f32_e32 v181, 1.0, v181
	v_add_f32_e32 v182, 1.0, v182
	v_add_f32_e32 v183, 1.0, v183
	v_add_f32_e32 v184, 1.0, v184
	v_add_f32_e32 v185, 1.0, v185
	v_rcp_f32_e32 v178, v178
	v_rcp_f32_e32 v179, v179
	v_rcp_f32_e32 v180, v180
	v_rcp_f32_e32 v181, v181
	v_rcp_f32_e32 v182, v182
	v_rcp_f32_e32 v183, v183
	v_rcp_f32_e32 v184, v184
	v_rcp_f32_e32 v185, v185
	v_mul_f32_e32 v178, v26, v178
	v_mul_f32_e32 v179, v27, v179
	v_mul_f32_e32 v180, v28, v180
	v_mul_f32_e32 v181, v29, v181
	v_mul_f32_e32 v182, v30, v182
	v_mul_f32_e32 v183, v31, v183
	v_mul_f32_e32 v184, v32, v184
	v_mul_f32_e32 v185, v33, v185
	v_fma_mixlo_f16 v178, v10, v178, 0
	v_fma_mixlo_f16 v179, v11, v179, 0
	v_fma_mixlo_f16 v180, v12, v180, 0
	v_fma_mixlo_f16 v181, v13, v181, 0
	v_fma_mixlo_f16 v182, v14, v182, 0
	v_fma_mixlo_f16 v183, v15, v183, 0
	v_fma_mixlo_f16 v184, v16, v184, 0
	v_fma_mixlo_f16 v185, v17, v185, 0
	global_store_short v186, v178, s[8:9]
	global_store_short v187, v179, s[8:9]
	global_store_short v188, v180, s[8:9]
	global_store_short v189, v181, s[8:9]
	global_store_short v190, v182, s[8:9]
	global_store_short v191, v183, s[8:9]
	global_store_short v192, v184, s[8:9]
	global_store_short v193, v185, s[8:9]

; DI int TIDX() { int t = threadIdx.x; asm volatile("" : "+v"(t)); return t; }
; template <class F>
; DI void epi_foreach(f32x16 (&acc)[2][2], int m0, int n0, F f) {
;   const int lane = TIDX() & 63, w = TIDX() >> 6, wm = w >> 1, wn = w & 1, hh = lane >> 5, c = lane & 31;
; #pragma unroll
;   for (int mi = 0; mi < 2; ++mi)
; #pragma unroll
;     for (int ni = 0; ni < 2; ++ni) f(m0 + wm * 64 + mi * 32 + 4 * hh, n0 + wn * 64 + ni * 32 + c, acc[mi][ni]);
; }
; DI void phase_gemm_plain(const h16* A, int lda, const h16* Bt, int K, h16* C, int ldc, int mt0, int mt1, int ntn, char* smem) {
;     ...
;     epi_foreach(acc, m0, n0, [&](int rbase, int n, const f32x16& v) {
; #pragma unroll
;       for (int i = 0; i < 16; ++i) C[(size_t)EROW(rbase, i) * ldc + n] = (h16)v[i];
;     });
.LBB0_90:
	v_mov_b32_e32 v0, v203
	s_waitcnt vmcnt(0)
	v_mov_b32_e32 v66, v203
	s_nop 7
	s_nop 7
	s_nop 7
	s_nop 4
	v_cvt_f16_f32_e32 v20, v20
	v_and_b32_e32 v67, 64, v66
	v_and_b32_e32 v69, 31, v0
	v_ashrrev_i32_e32 v66, 1, v66
	v_lshrrev_b32_e32 v0, 3, v0
	v_and_b32_e32 v66, 0xffffffc0, v66
	v_and_or_b32 v0, v0, 4, s6
	v_add_u32_e32 v68, v0, v66
	v_or3_b32 v66, v69, v67, s4
	v_cvt_f16_f32_e32 v0, v50
	v_ashrrev_i32_e32 v67, 31, v66
	v_ashrrev_i32_e32 v69, 31, v68
	v_lshl_add_u64 v[66:67], v[66:67], 1, s[0:1]
	v_lshlrev_b64 v[100:101], 11, v[68:69]
	v_lshl_add_u64 v[100:101], v[66:67], 0, v[100:101]
	v_or_b32_e32 v70, 1, v68
	v_or_b32_e32 v72, 2, v68
	v_cvt_f16_f32_e32 v69, v51
	global_store_short v[100:101], v0, off
	v_cvt_f16_f32_e32 v0, v52
	v_ashrrev_i32_e32 v71, 31, v70
	v_ashrrev_i32_e32 v73, 31, v72
	v_lshlrev_b64 v[50:51], 11, v[70:71]
	v_lshlrev_b64 v[70:71], 11, v[72:73]
	v_lshl_add_u64 v[50:51], v[66:67], 0, v[50:51]
	v_lshl_add_u64 v[70:71], v[66:67], 0, v[70:71]
	v_or_b32_e32 v74, 3, v68
	v_or_b32_e32 v76, 8, v68
	global_store_short v[50:51], v69, off
	v_cvt_f16_f32_e32 v69, v53
	global_store_short v[70:71], v0, off
	v_cvt_f16_f32_e32 v0, v54
	v_ashrrev_i32_e32 v75, 31, v74
	v_ashrrev_i32_e32 v77, 31, v76
	v_lshlrev_b64 v[52:53], 11, v[74:75]
	v_lshlrev_b64 v[72:73], 11, v[76:77]
	v_lshl_add_u64 v[52:53], v[66:67], 0, v[52:53]
	v_lshl_add_u64 v[72:73], v[66:67], 0, v[72:73]
	v_or_b32_e32 v78, 9, v68
	v_or_b32_e32 v80, 10, v68
	global_store_short v[52:53], v69, off
	v_cvt_f16_f32_e32 v69, v55
	global_store_short v[72:73], v0, off
	v_cvt_f16_f32_e32 v0, v56
	v_ashrrev_i32_e32 v79, 31, v78
	v_ashrrev_i32_e32 v81, 31, v80
	v_lshlrev_b64 v[54:55], 11, v[78:79]
	v_lshlrev_b64 v[74:75], 11, v[80:81]
	v_lshl_add_u64 v[54:55], v[66:67], 0, v[54:55]
	v_lshl_add_u64 v[74:75], v[66:67], 0, v[74:75]
	v_or_b32_e32 v82, 11, v68
	v_or_b32_e32 v84, 16, v68
	global_store_short v[54:55], v69, off
	v_cvt_f16_f32_e32 v69, v57
	global_store_short v[74:75], v0, off
	v_cvt_f16_f32_e32 v0, v58
	v_ashrrev_i32_e32 v83, 31, v82
	v_ashrrev_i32_e32 v85, 31, v84
	v_lshlrev_b64 v[56:57], 11, v[82:83]
	v_lshlrev_b64 v[76:77], 11, v[84:85]
	v_lshl_add_u64 v[56:57], v[66:67], 0, v[56:57]
	v_lshl_add_u64 v[76:77], v[66:67], 0, v[76:77]
	v_or_b32_e32 v86, 17, v68
	v_or_b32_e32 v88, 18, v68
	global_store_short v[56:57], v69, off
	v_cvt_f16_f32_e32 v69, v59
	global_store_short v[76:77], v0, off
	v_cvt_f16_f32_e32 v0, v60
	v_ashrrev_i32_e32 v87, 31, v86
	v_ashrrev_i32_e32 v89, 31, v88
	v_lshlrev_b64 v[58:59], 11, v[86:87]
	v_lshlrev_b64 v[78:79], 11, v[88:89]
	v_lshl_add_u64 v[58:59], v[66:67], 0, v[58:59]
	v_lshl_add_u64 v[78:79], v[66:67], 0, v[78:79]
	v_or_b32_e32 v90, 19, v68
	v_or_b32_e32 v92, 24, v68
	global_store_short v[58:59], v69, off
	v_cvt_f16_f32_e32 v69, v61
	global_store_short v[78:79], v0, off
	v_cvt_f16_f32_e32 v0, v62
	v_ashrrev_i32_e32 v91, 31, v90
	v_ashrrev_i32_e32 v93, 31, v92
	v_lshlrev_b64 v[60:61], 11, v[90:91]
	v_lshlrev_b64 v[80:81], 11, v[92:93]
	v_lshl_add_u64 v[60:61], v[66:67], 0, v[60:61]
	v_lshl_add_u64 v[80:81], v[66:67], 0, v[80:81]
	v_or_b32_e32 v94, 25, v68
	v_or_b32_e32 v96, 26, v68
	global_store_short v[60:61], v69, off
	v_cvt_f16_f32_e32 v69, v63
	global_store_short v[80:81], v0, off
	v_cvt_f16_f32_e32 v0, v64
	v_ashrrev_i32_e32 v95, 31, v94
	v_ashrrev_i32_e32 v97, 31, v96
	v_lshlrev_b64 v[62:63], 11, v[94:95]
	v_lshlrev_b64 v[82:83], 11, v[96:97]
	v_lshl_add_u64 v[62:63], v[66:67], 0, v[62:63]
	v_lshl_add_u64 v[82:83], v[66:67], 0, v[82:83]
	v_or_b32_e32 v98, 27, v68
	global_store_short v[62:63], v69, off
	v_cvt_f16_f32_e32 v69, v65
	global_store_short v[82:83], v0, off
	v_cvt_f16_f32_e32 v0, v34
	v_ashrrev_i32_e32 v99, 31, v98
	v_cvt_f16_f32_e32 v34, v35
	v_lshlrev_b64 v[64:65], 11, v[98:99]
	v_cvt_f16_f32_e32 v35, v36
	v_lshl_add_u64 v[64:65], v[66:67], 0, v[64:65]
	v_cvt_f16_f32_e32 v36, v37
	global_store_short v[64:65], v69, off
	global_store_short v[100:101], v0, off offset:64
	global_store_short v[50:51], v34, off offset:64
	global_store_short v[70:71], v35, off offset:64
	global_store_short v[52:53], v36, off offset:64
	v_cvt_f16_f32_e32 v0, v38
	v_cvt_f16_f32_e32 v34, v39
	v_cvt_f16_f32_e32 v35, v40
	v_cvt_f16_f32_e32 v36, v41
	global_store_short v[72:73], v0, off offset:64
	global_store_short v[54:55], v34, off offset:64
	global_store_short v[74:75], v35, off offset:64
	global_store_short v[56:57], v36, off offset:64
	v_cvt_f16_f32_e32 v0, v42
	v_cvt_f16_f32_e32 v34, v43
	v_cvt_f16_f32_e32 v35, v44
	v_cvt_f16_f32_e32 v36, v45
	global_store_short v[76:77], v0, off offset:64
	global_store_short v[58:59], v34, off offset:64
	global_store_short v[78:79], v35, off offset:64
	global_store_short v[60:61], v36, off offset:64
	v_cvt_f16_f32_e32 v0, v46
	v_cvt_f16_f32_e32 v34, v47
	v_cvt_f16_f32_e32 v35, v48
	v_cvt_f16_f32_e32 v36, v49
; DI int TIDX() { int t = threadIdx.x; asm volatile("" : "+v"(t)); return t; }
; template <class F>
; DI void epi_foreach(f32x16 (&acc)[2][2], int m0, int n0, F f) {
;   const int lane = TIDX() & 63, w = TIDX() >> 6, wm = w >> 1, wn = w & 1, hh = lane >> 5, c = lane & 31;
; #pragma unroll
;   for (int mi = 0; mi < 2; ++mi)
; #pragma unroll
;     for (int ni = 0; ni < 2; ++ni) f(m0 + wm * 64 + mi * 32 + 4 * hh, n0 + wn * 64 + ni * 32 + c, acc[mi][ni]);
; }
; DI void phase_gemm_plain(const h16* A, int lda, const h16* Bt, int K, h16* C, int ldc, int mt0, int mt1, int ntn, char* smem) {
;     ...
;     epi_foreach(acc, m0, n0, [&](int rbase, int n, const f32x16& v) {
; #pragma unroll
;       for (int i = 0; i < 16; ++i) C[(size_t)EROW(rbase, i) * ldc + n] = (h16)v[i];
;     });
	global_store_short v[80:81], v0, off offset:64
	global_store_short v[62:63], v34, off offset:64
	global_store_short v[82:83], v35, off offset:64
	global_store_short v[64:65], v36, off offset:64
	v_or_b32_e32 v34, 32, v68
	v_cvt_f16_f32_e32 v0, v18
	v_ashrrev_i32_e32 v35, 31, v34
	v_lshlrev_b64 v[34:35], 11, v[34:35]
	v_lshl_add_u64 v[34:35], v[66:67], 0, v[34:35]
	v_or_b32_e32 v36, 33, v68
	global_store_short v[34:35], v0, off
	v_cvt_f16_f32_e32 v0, v19
	v_ashrrev_i32_e32 v37, 31, v36
	v_or_b32_e32 v38, 34, v68
	v_lshlrev_b64 v[18:19], 11, v[36:37]
	v_ashrrev_i32_e32 v39, 31, v38
	v_lshl_add_u64 v[18:19], v[66:67], 0, v[18:19]
	v_or_b32_e32 v40, 35, v68
	global_store_short v[18:19], v0, off
	v_lshlrev_b64 v[36:37], 11, v[38:39]
	v_cvt_f16_f32_e32 v0, v21
	v_ashrrev_i32_e32 v41, 31, v40
	v_lshl_add_u64 v[36:37], v[66:67], 0, v[36:37]
	v_or_b32_e32 v42, 40, v68
	global_store_short v[36:37], v20, off
	v_lshlrev_b64 v[20:21], 11, v[40:41]
	v_cvt_f16_f32_e32 v22, v22
	v_ashrrev_i32_e32 v43, 31, v42
	v_lshl_add_u64 v[20:21], v[66:67], 0, v[20:21]
	v_or_b32_e32 v44, 41, v68
	global_store_short v[20:21], v0, off
	v_lshlrev_b64 v[38:39], 11, v[42:43]
	v_cvt_f16_f32_e32 v0, v23
	v_ashrrev_i32_e32 v45, 31, v44
	v_lshl_add_u64 v[38:39], v[66:67], 0, v[38:39]
	v_or_b32_e32 v46, 42, v68
	global_store_short v[38:39], v22, off
	v_lshlrev_b64 v[22:23], 11, v[44:45]
	v_cvt_f16_f32_e32 v24, v24
	v_ashrrev_i32_e32 v47, 31, v46
	v_lshl_add_u64 v[22:23], v[66:67], 0, v[22:23]
	v_or_b32_e32 v48, 43, v68
	global_store_short v[22:23], v0, off
	v_lshlrev_b64 v[40:41], 11, v[46:47]
	v_cvt_f16_f32_e32 v0, v25
	v_ashrrev_i32_e32 v49, 31, v48
	v_lshl_add_u64 v[40:41], v[66:67], 0, v[40:41]
	v_or_b32_e32 v50, 48, v68
	global_store_short v[40:41], v24, off
	v_lshlrev_b64 v[24:25], 11, v[48:49]
	v_cvt_f16_f32_e32 v26, v26
	v_ashrrev_i32_e32 v51, 31, v50
	v_lshl_add_u64 v[24:25], v[66:67], 0, v[24:25]
	v_or_b32_e32 v52, 49, v68
	global_store_short v[24:25], v0, off
	v_lshlrev_b64 v[42:43], 11, v[50:51]
	v_cvt_f16_f32_e32 v0, v27
	v_ashrrev_i32_e32 v53, 31, v52
	v_lshl_add_u64 v[42:43], v[66:67], 0, v[42:43]
	v_or_b32_e32 v54, 50, v68
	global_store_short v[42:43], v26, off
	v_lshlrev_b64 v[26:27], 11, v[52:53]
	v_cvt_f16_f32_e32 v28, v28
	v_ashrrev_i32_e32 v55, 31, v54
	v_lshl_add_u64 v[26:27], v[66:67], 0, v[26:27]
	v_or_b32_e32 v56, 51, v68
	global_store_short v[26:27], v0, off
	v_lshlrev_b64 v[44:45], 11, v[54:55]
	v_cvt_f16_f32_e32 v0, v29
	v_ashrrev_i32_e32 v57, 31, v56
	v_lshl_add_u64 v[44:45], v[66:67], 0, v[44:45]
	v_or_b32_e32 v58, 56, v68
	global_store_short v[44:45], v28, off
	v_lshlrev_b64 v[28:29], 11, v[56:57]
	v_cvt_f16_f32_e32 v30, v30
	v_ashrrev_i32_e32 v59, 31, v58
	v_lshl_add_u64 v[28:29], v[66:67], 0, v[28:29]
	v_or_b32_e32 v60, 57, v68
	global_store_short v[28:29], v0, off
	v_lshlrev_b64 v[46:47], 11, v[58:59]
	v_cvt_f16_f32_e32 v0, v31
	v_ashrrev_i32_e32 v61, 31, v60
	v_lshl_add_u64 v[46:47], v[66:67], 0, v[46:47]
	v_or_b32_e32 v62, 58, v68
	global_store_short v[46:47], v30, off
	v_lshlrev_b64 v[30:31], 11, v[60:61]
	v_cvt_f16_f32_e32 v32, v32
	v_ashrrev_i32_e32 v63, 31, v62
	v_lshl_add_u64 v[30:31], v[66:67], 0, v[30:31]
	v_or_b32_e32 v64, 59, v68
	global_store_short v[30:31], v0, off
	v_lshlrev_b64 v[48:49], 11, v[62:63]
	v_cvt_f16_f32_e32 v0, v33
	v_ashrrev_i32_e32 v65, 31, v64
	v_lshl_add_u64 v[48:49], v[66:67], 0, v[48:49]
	global_store_short v[48:49], v32, off
	v_lshlrev_b64 v[32:33], 11, v[64:65]
	v_lshl_add_u64 v[32:33], v[66:67], 0, v[32:33]
	v_cvt_f16_f32_e32 v2, v2
	global_store_short v[32:33], v0, off
	v_cvt_f16_f32_e32 v0, v4
	v_cvt_f16_f32_e32 v3, v3
	global_store_short v[34:35], v2, off offset:64
	global_store_short v[18:19], v3, off offset:64
	v_cvt_f16_f32_e32 v2, v5
	global_store_short v[36:37], v0, off offset:64
	v_cvt_f16_f32_e32 v0, v6
	v_cvt_f16_f32_e32 v3, v7
	global_store_short v[20:21], v2, off offset:64
	v_cvt_f16_f32_e32 v2, v8
	global_store_short v[38:39], v0, off offset:64
	global_store_short v[22:23], v3, off offset:64
	v_cvt_f16_f32_e32 v0, v9
	v_cvt_f16_f32_e32 v3, v11
	global_store_short v[40:41], v2, off offset:64
	v_cvt_f16_f32_e32 v2, v10
	global_store_short v[24:25], v0, off offset:64
	v_cvt_f16_f32_e32 v0, v12
	global_store_short v[42:43], v2, off offset:64
	global_store_short v[26:27], v3, off offset:64
	v_cvt_f16_f32_e32 v2, v13
	global_store_short v[44:45], v0, off offset:64
	v_cvt_f16_f32_e32 v0, v14
	v_cvt_f16_f32_e32 v3, v15
	global_store_short v[28:29], v2, off offset:64
	v_cvt_f16_f32_e32 v2, v16
	global_store_short v[46:47], v0, off offset:64
	global_store_short v[30:31], v3, off offset:64
	v_cvt_f16_f32_e32 v0, v17
	v_readlane_b32 s2, v252, 63
	s_add_i32 s15, s15, s2
	s_cmp_ge_i32 s15, s14
	global_store_short v[48:49], v2, off offset:64
	global_store_short v[32:33], v0, off offset:64
	s_cbranch_scc1 .LBB0_97
